# whole third round of the weight-copy tail (320 items: last W_ffn_down k-blocks + W_ple_gate) moved to the start of P2, waves 0-4 of the 64 class-0 workgroups; the P1 tail is two full rounds
# baseline (speedup 1.0000x reference)
; __device__ __forceinline__ void convert_weights(const Args& args, int first, int last, int worker, int nworkers, int lane) {
;     ...
;     for (;;) {
;         const int nx = it + nworkers; const bool more = nx < last;
;         WItem nxt = cur; f32x4 vn[WR];
;         if (more) { nxt = witem_decode(args, nx, lane); witem_load(nxt, vn); }
;         witem_store(cur, v);
;         if (!more) break;
; #pragma unroll
;         for (int j = 0; j < WR; ++j) v[j] = vn[j];
;         cur = nxt; it = nx;
.LBB0_429:
	s_add_i32 s28, s33, 0x400
	s_cmpk_gt_i32 s33, 0x8ff
	s_cselect_b64 s[8:9], -1, 0
	s_cmpk_lt_i32 s33, 0x7c0
	s_cbranch_scc1 .Lcv3_keep
	s_cmpk_gt_i32 s33, 0xbbf
	s_cbranch_scc1 .Lcv3_keep
	s_add_i32 s98, s33, 0xfffff840
	s_lshr_b32 s99, s98, 1
	s_and_b32 s99, s99, 0xfffffffc
	s_and_b32 s28, s98, 3
	s_add_i32 s28, s28, s99
	s_addk_i32 s28, 0xbc0
	s_add_i32 s33, s28, 0xfffffc00
	s_and_b32 s99, s98, 4
	s_cselect_b32 s99, 1, 0
	s_mov_b32 s99, 1
	s_cmp_lg_u32 s99, 0
	s_cselect_b64 s[8:9], -1, 0

; __device__ __forceinline__ void convert_weights(const Args& args, int first, int last, int worker, int nworkers, int lane) {
;     int it = first + worker;
;     if (it >= last) return;
; __global__ void __launch_bounds__(NWAVES * 64, 2) fwd_kernel(Args args) {
;     ...
;         for (int v = vcu; v < nattn; v += G) {
;             const int bh = v >> 2, s = v & 3;
;             for (int i = 0; i < 2; ++i) {
;                 const int qb = i == 0 ? s : 7 - s;
;                 attn_body::attn_unit<8>(bh / NHEAD, bh % NHEAD, qb, MIX + AW, Kb, Vb, (dry ? dmy_mix : MIX) + AW, kms, (char*)lds_raw);
.LBB0_523:
.LBB0_524:
	s_cmp_lg_u32 s100, 0
	s_cbranch_scc1 .Lw_done
	s_and_b64 vcc, exec, s[88:89]
	s_cbranch_vccz .Lw_done
	s_and_b32 s98, s85, 3
	s_cmp_lg_u32 s98, 0
	s_cbranch_scc1 .Lw_done
	v_readlane_b32 s98, v254, 22
	s_nop 0
	s_cmp_gt_u32 s98, 4
	s_cbranch_scc1 .Lw_done
	s_lshr_b32 s25, s85, 2
	s_mul_i32 s25, s25, 5
	s_add_i32 s25, s25, s98
	s_addk_i32 s25, 0x800
	s_mov_b32 s100, 1
	s_branch .Lw_go
